# GEMM K-loop heads at 4 mod 64 bytes (.p2align 6 + s_nop)
# baseline (speedup 1.0000x reference)
.LBB0_162:
	s_ashr_i32 s19, s18, 31
	s_lshl_b64 s[20:21], s[18:19], 19
	s_add_u32 s20, s8, s20
	s_addc_u32 s21, s9, s21
	s_and_b64 s[22:23], s[4:5], exec
	s_cselect_b32 s19, s21, s27
	s_cselect_b32 s51, s20, s26
	s_ashr_i32 s17, s16, 31
	s_lshl_b64 s[22:23], s[16:17], 19
	s_add_u32 s22, s31, s22
	s_addc_u32 s23, s34, s23
	s_and_b64 s[28:29], s[4:5], exec
	s_cselect_b32 s17, s23, s25
	s_cselect_b32 s52, s22, s24
	s_add_u32 s53, s24, 0x100
	s_addc_u32 s54, s25, 0
	s_add_u32 s24, s26, 0x40080
	v_mov_b32_e32 v0, 0
	s_addc_u32 s25, s27, 0
	s_mov_b32 s55, -2
	v_mov_b32_e32 v1, v0
	v_mov_b32_e32 v2, v0
	v_mov_b32_e32 v3, v0
	v_mov_b32_e32 v4, v0
	v_mov_b32_e32 v5, v0
	v_mov_b32_e32 v6, v0
	v_mov_b32_e32 v7, v0
	v_mov_b32_e32 v16, v0
	v_mov_b32_e32 v17, v0
	s_waitcnt vmcnt(0)
	v_mov_b32_e32 v18, v0
	v_mov_b32_e32 v19, v0
	v_mov_b32_e32 v20, v0
	v_mov_b32_e32 v21, v0
	v_mov_b32_e32 v22, v0
	v_mov_b32_e32 v23, v0
	v_mov_b32_e32 v32, v0
	v_mov_b32_e32 v33, v0
	v_mov_b32_e32 v34, v0
	v_mov_b32_e32 v35, v0
	v_mov_b32_e32 v36, v0
	v_mov_b32_e32 v37, v0
	v_mov_b32_e32 v38, v0
	v_mov_b32_e32 v39, v0
	v_mov_b32_e32 v48, v0
	v_mov_b32_e32 v49, v0
	v_mov_b32_e32 v50, v0
	v_mov_b32_e32 v51, v0
	v_mov_b32_e32 v52, v0
	v_mov_b32_e32 v53, v0
	v_mov_b32_e32 v54, v0
	v_mov_b32_e32 v55, v0
	v_mov_b32_e32 v8, v0
	v_mov_b32_e32 v9, v0
	v_mov_b32_e32 v10, v0
	v_mov_b32_e32 v11, v0
	v_mov_b32_e32 v12, v0
	v_mov_b32_e32 v13, v0
	v_mov_b32_e32 v14, v0
	v_mov_b32_e32 v15, v0
	v_mov_b32_e32 v24, v0
	v_mov_b32_e32 v25, v0
	v_mov_b32_e32 v26, v0
	v_mov_b32_e32 v27, v0
	v_mov_b32_e32 v28, v0
	v_mov_b32_e32 v29, v0
	v_mov_b32_e32 v30, v0
	v_mov_b32_e32 v31, v0
	v_mov_b32_e32 v40, v0
	v_mov_b32_e32 v41, v0
	v_mov_b32_e32 v42, v0
	v_mov_b32_e32 v43, v0
	v_mov_b32_e32 v44, v0
	v_mov_b32_e32 v45, v0
	v_mov_b32_e32 v46, v0
	v_mov_b32_e32 v47, v0
	v_mov_b32_e32 v56, v0
	v_mov_b32_e32 v57, v0
	v_mov_b32_e32 v58, v0
	v_mov_b32_e32 v59, v0
	v_mov_b32_e32 v60, v0
	v_mov_b32_e32 v61, v0
	v_mov_b32_e32 v62, v0
	v_mov_b32_e32 v63, v0
	v_mov_b32_e32 v64, v0
	v_mov_b32_e32 v65, v0
	v_mov_b32_e32 v66, v0
	v_mov_b32_e32 v67, v0
	v_mov_b32_e32 v68, v0
	v_mov_b32_e32 v69, v0
	v_mov_b32_e32 v70, v0
	v_mov_b32_e32 v71, v0
	v_mov_b32_e32 v80, v0
	v_mov_b32_e32 v81, v0
	v_mov_b32_e32 v82, v0
	v_mov_b32_e32 v83, v0
	v_mov_b32_e32 v84, v0
	v_mov_b32_e32 v85, v0
	v_mov_b32_e32 v86, v0
	v_mov_b32_e32 v87, v0
	v_mov_b32_e32 v96, v0
	v_mov_b32_e32 v97, v0
	v_mov_b32_e32 v98, v0
	v_mov_b32_e32 v99, v0
	v_mov_b32_e32 v100, v0
	v_mov_b32_e32 v101, v0
	v_mov_b32_e32 v102, v0
	v_mov_b32_e32 v103, v0
	v_mov_b32_e32 v112, v0
	v_mov_b32_e32 v113, v0
	v_mov_b32_e32 v114, v0
	v_mov_b32_e32 v115, v0
	v_mov_b32_e32 v116, v0
	v_mov_b32_e32 v117, v0
	v_mov_b32_e32 v118, v0
	v_mov_b32_e32 v119, v0
	v_mov_b32_e32 v72, v0
	v_mov_b32_e32 v73, v0
	v_mov_b32_e32 v74, v0
	v_mov_b32_e32 v75, v0
	v_mov_b32_e32 v76, v0
	v_mov_b32_e32 v77, v0
	v_mov_b32_e32 v78, v0
	v_mov_b32_e32 v79, v0
	v_mov_b32_e32 v88, v0
	v_mov_b32_e32 v89, v0
	v_mov_b32_e32 v90, v0
	v_mov_b32_e32 v91, v0
	v_mov_b32_e32 v92, v0
	v_mov_b32_e32 v93, v0
	v_mov_b32_e32 v94, v0
	v_mov_b32_e32 v95, v0
	v_mov_b32_e32 v104, v0
	v_mov_b32_e32 v105, v0
	v_mov_b32_e32 v106, v0
	v_mov_b32_e32 v107, v0
	v_mov_b32_e32 v108, v0
	v_mov_b32_e32 v109, v0
	v_mov_b32_e32 v110, v0
	v_mov_b32_e32 v111, v0
	v_mov_b32_e32 v120, v0
	v_mov_b32_e32 v121, v0
	v_mov_b32_e32 v122, v0
	v_mov_b32_e32 v123, v0
	v_mov_b32_e32 v124, v0
	v_mov_b32_e32 v125, v0
	v_mov_b32_e32 v126, v0
	v_mov_b32_e32 v127, v0
	v_add_u32_e32 v204, 0x80, v128
	v_add_u32_e32 v205, 0x80, v130
	v_add_u32_e32 v220, 0x80, v132
	v_add_u32_e32 v221, 0x80, v134
	.p2align	6
	s_nop 0

.LBB0_605:
	s_ashr_i32 s21, s20, 31
	s_lshl_b64 s[22:23], s[20:21], 19
	s_add_u32 s22, s39, s22
	s_addc_u32 s23, s40, s23
	s_and_b64 s[24:25], s[6:7], exec
	s_cselect_b32 s21, s23, s29
	s_cselect_b32 s27, s22, s28
	s_ashr_i32 s19, s18, 31
	s_lshl_b64 s[24:25], s[18:19], 19
	s_add_u32 s24, s41, s24
	s_addc_u32 s25, s42, s25
	s_and_b64 s[34:35], s[6:7], exec
	s_cselect_b32 s19, s25, s31
	s_cselect_b32 s55, s24, s30
	s_add_u32 s56, s30, 0x100
	v_mov_b32_e32 v0, 0
	s_addc_u32 s57, s31, 0
	s_mov_b32 s58, -2
	v_mov_b32_e32 v1, v0
	v_mov_b32_e32 v2, v0
	v_mov_b32_e32 v3, v0
	v_mov_b32_e32 v4, v0
	v_mov_b32_e32 v5, v0
	v_mov_b32_e32 v6, v0
	v_mov_b32_e32 v7, v0
	v_mov_b32_e32 v16, v0
	v_mov_b32_e32 v17, v0
	v_mov_b32_e32 v18, v0
	v_mov_b32_e32 v19, v0
	v_mov_b32_e32 v20, v0
	v_mov_b32_e32 v21, v0
	v_mov_b32_e32 v22, v0
	v_mov_b32_e32 v23, v0
	v_mov_b32_e32 v32, v0
	v_mov_b32_e32 v33, v0
	v_mov_b32_e32 v34, v0
	v_mov_b32_e32 v35, v0
	v_mov_b32_e32 v36, v0
	v_mov_b32_e32 v37, v0
	v_mov_b32_e32 v38, v0
	v_mov_b32_e32 v39, v0
	v_mov_b32_e32 v48, v0
	v_mov_b32_e32 v49, v0
	v_mov_b32_e32 v50, v0
	v_mov_b32_e32 v51, v0
	v_mov_b32_e32 v52, v0
	v_mov_b32_e32 v53, v0
	v_mov_b32_e32 v54, v0
	v_mov_b32_e32 v55, v0
	v_mov_b32_e32 v8, v0
	v_mov_b32_e32 v9, v0
	v_mov_b32_e32 v10, v0
	v_mov_b32_e32 v11, v0
	v_mov_b32_e32 v12, v0
	v_mov_b32_e32 v13, v0
	v_mov_b32_e32 v14, v0
	v_mov_b32_e32 v15, v0
	v_mov_b32_e32 v24, v0
	v_mov_b32_e32 v25, v0
	v_mov_b32_e32 v26, v0
	v_mov_b32_e32 v27, v0
	v_mov_b32_e32 v28, v0
	v_mov_b32_e32 v29, v0
	v_mov_b32_e32 v30, v0
	v_mov_b32_e32 v31, v0
	v_mov_b32_e32 v40, v0
	v_mov_b32_e32 v41, v0
	v_mov_b32_e32 v42, v0
	v_mov_b32_e32 v43, v0
	v_mov_b32_e32 v44, v0
	v_mov_b32_e32 v45, v0
	v_mov_b32_e32 v46, v0
	v_mov_b32_e32 v47, v0
	v_mov_b32_e32 v56, v0
	v_mov_b32_e32 v57, v0
	v_mov_b32_e32 v58, v0
	v_mov_b32_e32 v59, v0
	v_mov_b32_e32 v60, v0
	v_mov_b32_e32 v61, v0
	v_mov_b32_e32 v62, v0
	v_mov_b32_e32 v63, v0
	v_mov_b32_e32 v64, v0
	v_mov_b32_e32 v65, v0
	v_mov_b32_e32 v66, v0
	v_mov_b32_e32 v67, v0
	v_mov_b32_e32 v68, v0
	v_mov_b32_e32 v69, v0
	v_mov_b32_e32 v70, v0
	v_mov_b32_e32 v71, v0
	v_mov_b32_e32 v80, v0
	v_mov_b32_e32 v81, v0
	v_mov_b32_e32 v82, v0
	v_mov_b32_e32 v83, v0
	v_mov_b32_e32 v84, v0
	v_mov_b32_e32 v85, v0
	v_mov_b32_e32 v86, v0
	v_mov_b32_e32 v87, v0
	v_mov_b32_e32 v96, v0
	v_mov_b32_e32 v97, v0
	v_mov_b32_e32 v98, v0
	v_mov_b32_e32 v99, v0
	v_mov_b32_e32 v100, v0
	v_mov_b32_e32 v101, v0
	v_mov_b32_e32 v102, v0
	v_mov_b32_e32 v103, v0
	v_mov_b32_e32 v112, v0
	v_mov_b32_e32 v113, v0
	v_mov_b32_e32 v114, v0
	v_mov_b32_e32 v115, v0
	v_mov_b32_e32 v116, v0
	v_mov_b32_e32 v117, v0
	v_mov_b32_e32 v118, v0
	v_mov_b32_e32 v119, v0
	v_mov_b32_e32 v72, v0
	v_mov_b32_e32 v73, v0
	v_mov_b32_e32 v74, v0
	v_mov_b32_e32 v75, v0
	v_mov_b32_e32 v76, v0
	v_mov_b32_e32 v77, v0
	v_mov_b32_e32 v78, v0
	v_mov_b32_e32 v79, v0
	v_mov_b32_e32 v88, v0
	v_mov_b32_e32 v89, v0
	v_mov_b32_e32 v90, v0
	v_mov_b32_e32 v91, v0
	v_mov_b32_e32 v92, v0
	v_mov_b32_e32 v93, v0
	v_mov_b32_e32 v94, v0
	v_mov_b32_e32 v95, v0
	v_mov_b32_e32 v104, v0
	v_mov_b32_e32 v105, v0
	v_mov_b32_e32 v106, v0
	v_mov_b32_e32 v107, v0
	v_mov_b32_e32 v108, v0
	v_mov_b32_e32 v109, v0
	v_mov_b32_e32 v110, v0
	v_mov_b32_e32 v111, v0
	v_mov_b32_e32 v120, v0
	v_mov_b32_e32 v121, v0
	v_mov_b32_e32 v122, v0
	v_mov_b32_e32 v123, v0
	v_mov_b32_e32 v124, v0
	v_mov_b32_e32 v125, v0
	v_mov_b32_e32 v126, v0
	v_mov_b32_e32 v127, v0
	v_add_u32_e32 v212, 0x80, v128
	v_add_u32_e32 v213, 0x80, v130
	.p2align	6
	s_nop 0

.LBB0_698:
	s_ashr_i32 s21, s20, 31
	s_lshl_b64 s[22:23], s[20:21], 19
	s_add_u32 s22, s8, s22
	s_addc_u32 s23, s9, s23
	s_and_b64 s[24:25], s[4:5], exec
	s_cselect_b32 s21, s23, s29
	s_cselect_b32 s49, s22, s28
	s_ashr_i32 s19, s18, 31
	s_lshl_b64 s[24:25], s[18:19], 19
	s_add_u32 s24, s36, s24
	s_addc_u32 s25, s37, s25
	s_and_b64 s[30:31], s[4:5], exec
	s_cselect_b32 s19, s25, s27
	s_cselect_b32 s50, s24, s26
	s_add_u32 s51, s26, 0x100
	s_addc_u32 s52, s27, 0
	s_add_u32 s26, s28, 0x40080
	v_mov_b32_e32 v0, 0
	s_addc_u32 s27, s29, 0
	s_mov_b32 s53, -2
	v_mov_b32_e32 v1, v0
	v_mov_b32_e32 v2, v0
	v_mov_b32_e32 v3, v0
	v_mov_b32_e32 v4, v0
	v_mov_b32_e32 v5, v0
	v_mov_b32_e32 v6, v0
	v_mov_b32_e32 v7, v0
	v_mov_b32_e32 v16, v0
	v_mov_b32_e32 v17, v0
	v_mov_b32_e32 v18, v0
	v_mov_b32_e32 v19, v0
	v_mov_b32_e32 v20, v0
	v_mov_b32_e32 v21, v0
	v_mov_b32_e32 v22, v0
	v_mov_b32_e32 v23, v0
	v_mov_b32_e32 v32, v0
	v_mov_b32_e32 v33, v0
	v_mov_b32_e32 v34, v0
	v_mov_b32_e32 v35, v0
	v_mov_b32_e32 v36, v0
	v_mov_b32_e32 v37, v0
	v_mov_b32_e32 v38, v0
	v_mov_b32_e32 v39, v0
	v_mov_b32_e32 v48, v0
	v_mov_b32_e32 v49, v0
	v_mov_b32_e32 v50, v0
	v_mov_b32_e32 v51, v0
	v_mov_b32_e32 v52, v0
	v_mov_b32_e32 v53, v0
	v_mov_b32_e32 v54, v0
	v_mov_b32_e32 v55, v0
	v_mov_b32_e32 v8, v0
	v_mov_b32_e32 v9, v0
	v_mov_b32_e32 v10, v0
	v_mov_b32_e32 v11, v0
	v_mov_b32_e32 v12, v0
	v_mov_b32_e32 v13, v0
	v_mov_b32_e32 v14, v0
	v_mov_b32_e32 v15, v0
	v_mov_b32_e32 v24, v0
	v_mov_b32_e32 v25, v0
	v_mov_b32_e32 v26, v0
	v_mov_b32_e32 v27, v0
	v_mov_b32_e32 v28, v0
	v_mov_b32_e32 v29, v0
	v_mov_b32_e32 v30, v0
	v_mov_b32_e32 v31, v0
	v_mov_b32_e32 v40, v0
	v_mov_b32_e32 v41, v0
	v_mov_b32_e32 v42, v0
	v_mov_b32_e32 v43, v0
	v_mov_b32_e32 v44, v0
	v_mov_b32_e32 v45, v0
	v_mov_b32_e32 v46, v0
	v_mov_b32_e32 v47, v0
	v_mov_b32_e32 v56, v0
	v_mov_b32_e32 v57, v0
	v_mov_b32_e32 v58, v0
	v_mov_b32_e32 v59, v0
	v_mov_b32_e32 v60, v0
	v_mov_b32_e32 v61, v0
	v_mov_b32_e32 v62, v0
	v_mov_b32_e32 v63, v0
	v_mov_b32_e32 v64, v0
	v_mov_b32_e32 v65, v0
	v_mov_b32_e32 v66, v0
	v_mov_b32_e32 v67, v0
	v_mov_b32_e32 v68, v0
	v_mov_b32_e32 v69, v0
	v_mov_b32_e32 v70, v0
	v_mov_b32_e32 v71, v0
	v_mov_b32_e32 v80, v0
	v_mov_b32_e32 v81, v0
	v_mov_b32_e32 v82, v0
	v_mov_b32_e32 v83, v0
	v_mov_b32_e32 v84, v0
	v_mov_b32_e32 v85, v0
	v_mov_b32_e32 v86, v0
	v_mov_b32_e32 v87, v0
	v_mov_b32_e32 v96, v0
	v_mov_b32_e32 v97, v0
	v_mov_b32_e32 v98, v0
	v_mov_b32_e32 v99, v0
	v_mov_b32_e32 v100, v0
	v_mov_b32_e32 v101, v0
	v_mov_b32_e32 v102, v0
	v_mov_b32_e32 v103, v0
	v_mov_b32_e32 v112, v0
	v_mov_b32_e32 v113, v0
	v_mov_b32_e32 v114, v0
	v_mov_b32_e32 v115, v0
	v_mov_b32_e32 v116, v0
	v_mov_b32_e32 v117, v0
	v_mov_b32_e32 v118, v0
	v_mov_b32_e32 v119, v0
	v_mov_b32_e32 v72, v0
	v_mov_b32_e32 v73, v0
	v_mov_b32_e32 v74, v0
	v_mov_b32_e32 v75, v0
	v_mov_b32_e32 v76, v0
	v_mov_b32_e32 v77, v0
	v_mov_b32_e32 v78, v0
	v_mov_b32_e32 v79, v0
	v_mov_b32_e32 v88, v0
	v_mov_b32_e32 v89, v0
	v_mov_b32_e32 v90, v0
	v_mov_b32_e32 v91, v0
	v_mov_b32_e32 v92, v0
	v_mov_b32_e32 v93, v0
	v_mov_b32_e32 v94, v0
	v_mov_b32_e32 v95, v0
	v_mov_b32_e32 v104, v0
	v_mov_b32_e32 v105, v0
	v_mov_b32_e32 v106, v0
	v_mov_b32_e32 v107, v0
	v_mov_b32_e32 v108, v0
	v_mov_b32_e32 v109, v0
	v_mov_b32_e32 v110, v0
	v_mov_b32_e32 v111, v0
	v_mov_b32_e32 v120, v0
	v_mov_b32_e32 v121, v0
	v_mov_b32_e32 v122, v0
	v_mov_b32_e32 v123, v0
	v_mov_b32_e32 v124, v0
	v_mov_b32_e32 v125, v0
	v_mov_b32_e32 v126, v0
	v_mov_b32_e32 v127, v0
	v_add_u32_e32 v204, 0x80, v128
	v_add_u32_e32 v205, 0x80, v130
	v_add_u32_e32 v220, 0x80, v132
	v_add_u32_e32 v221, 0x80, v134
	.p2align	6
	s_nop 0

.LBB0_777:
	s_ashr_i32 s21, s20, 31
	s_lshl_b64 s[22:23], s[20:21], 21
	s_add_u32 s22, s39, s22
	s_addc_u32 s23, s40, s23
	s_and_b64 s[24:25], s[6:7], exec
	s_cselect_b32 s21, s23, s29
	s_cselect_b32 s27, s22, s28
	s_ashr_i32 s19, s18, 31
	s_lshl_b64 s[24:25], s[18:19], 21
	s_add_u32 s24, s41, s24
	s_addc_u32 s25, s42, s25
	s_and_b64 s[34:35], s[6:7], exec
	s_cselect_b32 s19, s25, s31
	s_cselect_b32 s55, s24, s30
	s_add_u32 s56, s30, 0x100
	v_mov_b32_e32 v0, 0
	s_addc_u32 s57, s31, 0
	s_mov_b32 s58, -2
	v_mov_b32_e32 v1, v0
	v_mov_b32_e32 v2, v0
	v_mov_b32_e32 v3, v0
	v_mov_b32_e32 v4, v0
	v_mov_b32_e32 v5, v0
	v_mov_b32_e32 v6, v0
	v_mov_b32_e32 v7, v0
	v_mov_b32_e32 v16, v0
	v_mov_b32_e32 v17, v0
	v_mov_b32_e32 v18, v0
	v_mov_b32_e32 v19, v0
	v_mov_b32_e32 v20, v0
	v_mov_b32_e32 v21, v0
	v_mov_b32_e32 v22, v0
	v_mov_b32_e32 v23, v0
	v_mov_b32_e32 v32, v0
	v_mov_b32_e32 v33, v0
	v_mov_b32_e32 v34, v0
	v_mov_b32_e32 v35, v0
	v_mov_b32_e32 v36, v0
	v_mov_b32_e32 v37, v0
	v_mov_b32_e32 v38, v0
	v_mov_b32_e32 v39, v0
	v_mov_b32_e32 v48, v0
	v_mov_b32_e32 v49, v0
	v_mov_b32_e32 v50, v0
	v_mov_b32_e32 v51, v0
	v_mov_b32_e32 v52, v0
	v_mov_b32_e32 v53, v0
	v_mov_b32_e32 v54, v0
	v_mov_b32_e32 v55, v0
	v_mov_b32_e32 v8, v0
	v_mov_b32_e32 v9, v0
	v_mov_b32_e32 v10, v0
	v_mov_b32_e32 v11, v0
	v_mov_b32_e32 v12, v0
	v_mov_b32_e32 v13, v0
	v_mov_b32_e32 v14, v0
	v_mov_b32_e32 v15, v0
	v_mov_b32_e32 v24, v0
	v_mov_b32_e32 v25, v0
	v_mov_b32_e32 v26, v0
	v_mov_b32_e32 v27, v0
	v_mov_b32_e32 v28, v0
	v_mov_b32_e32 v29, v0
	v_mov_b32_e32 v30, v0
	v_mov_b32_e32 v31, v0
	v_mov_b32_e32 v40, v0
	v_mov_b32_e32 v41, v0
	v_mov_b32_e32 v42, v0
	v_mov_b32_e32 v43, v0
	v_mov_b32_e32 v44, v0
	v_mov_b32_e32 v45, v0
	v_mov_b32_e32 v46, v0
	v_mov_b32_e32 v47, v0
	v_mov_b32_e32 v56, v0
	v_mov_b32_e32 v57, v0
	v_mov_b32_e32 v58, v0
	v_mov_b32_e32 v59, v0
	v_mov_b32_e32 v60, v0
	v_mov_b32_e32 v61, v0
	v_mov_b32_e32 v62, v0
	v_mov_b32_e32 v63, v0
	v_mov_b32_e32 v64, v0
	v_mov_b32_e32 v65, v0
	v_mov_b32_e32 v66, v0
	v_mov_b32_e32 v67, v0
	v_mov_b32_e32 v68, v0
	v_mov_b32_e32 v69, v0
	v_mov_b32_e32 v70, v0
	v_mov_b32_e32 v71, v0
	v_mov_b32_e32 v80, v0
	v_mov_b32_e32 v81, v0
	v_mov_b32_e32 v82, v0
	v_mov_b32_e32 v83, v0
	v_mov_b32_e32 v84, v0
	v_mov_b32_e32 v85, v0
	v_mov_b32_e32 v86, v0
	v_mov_b32_e32 v87, v0
	v_mov_b32_e32 v96, v0
	v_mov_b32_e32 v97, v0
	v_mov_b32_e32 v98, v0
	v_mov_b32_e32 v99, v0
	v_mov_b32_e32 v100, v0
	v_mov_b32_e32 v101, v0
	v_mov_b32_e32 v102, v0
	v_mov_b32_e32 v103, v0
	v_mov_b32_e32 v112, v0
	v_mov_b32_e32 v113, v0
	v_mov_b32_e32 v114, v0
	v_mov_b32_e32 v115, v0
	v_mov_b32_e32 v116, v0
	v_mov_b32_e32 v117, v0
	v_mov_b32_e32 v118, v0
	v_mov_b32_e32 v119, v0
	v_mov_b32_e32 v72, v0
	v_mov_b32_e32 v73, v0
	v_mov_b32_e32 v74, v0
	v_mov_b32_e32 v75, v0
	v_mov_b32_e32 v76, v0
	v_mov_b32_e32 v77, v0
	v_mov_b32_e32 v78, v0
	v_mov_b32_e32 v79, v0
	v_mov_b32_e32 v88, v0
	v_mov_b32_e32 v89, v0
	v_mov_b32_e32 v90, v0
	v_mov_b32_e32 v91, v0
	v_mov_b32_e32 v92, v0
	v_mov_b32_e32 v93, v0
	v_mov_b32_e32 v94, v0
	v_mov_b32_e32 v95, v0
	v_mov_b32_e32 v104, v0
	v_mov_b32_e32 v105, v0
	v_mov_b32_e32 v106, v0
	v_mov_b32_e32 v107, v0
	v_mov_b32_e32 v108, v0
	v_mov_b32_e32 v109, v0
	v_mov_b32_e32 v110, v0
	v_mov_b32_e32 v111, v0
	v_mov_b32_e32 v120, v0
	v_mov_b32_e32 v121, v0
	v_mov_b32_e32 v122, v0
	v_mov_b32_e32 v123, v0
	v_mov_b32_e32 v124, v0
	v_mov_b32_e32 v125, v0
	v_mov_b32_e32 v126, v0
	v_mov_b32_e32 v127, v0
	v_add_u32_e32 v212, 0x80, v128
	v_add_u32_e32 v213, 0x80, v130
	.p2align	6
	s_nop 0

.LBB0_894:
	s_ashr_i32 s29, s28, 31
	s_lshl_b64 s[30:31], s[28:29], 19
	s_add_u32 s30, s8, s30
	s_addc_u32 s31, s9, s31
	s_and_b64 s[34:35], s[6:7], exec
	s_cselect_b32 s3, s31, s39
	s_cselect_b32 s29, s30, s38
	s_ashr_i32 s27, s26, 31
	s_lshl_b64 s[34:35], s[26:27], 19
	s_add_u32 s34, s43, s34
	s_addc_u32 s35, s44, s35
	s_and_b64 s[40:41], s[6:7], exec
	s_cselect_b32 s27, s35, s37
	s_cselect_b32 s58, s34, s36
	s_add_u32 s59, s36, 0x100
	s_addc_u32 s60, s37, 0
	s_add_u32 s36, s38, 0x40080
	v_mov_b32_e32 v0, 0
	s_addc_u32 s37, s39, 0
	s_mov_b32 s61, -2
	v_mov_b32_e32 v1, v0
	v_mov_b32_e32 v2, v0
	v_mov_b32_e32 v3, v0
	v_mov_b32_e32 v4, v0
	v_mov_b32_e32 v5, v0
	v_mov_b32_e32 v6, v0
	v_mov_b32_e32 v7, v0
	v_mov_b32_e32 v16, v0
	v_mov_b32_e32 v17, v0
	v_mov_b32_e32 v18, v0
	v_mov_b32_e32 v19, v0
	v_mov_b32_e32 v20, v0
	v_mov_b32_e32 v21, v0
	v_mov_b32_e32 v22, v0
	v_mov_b32_e32 v23, v0
	v_mov_b32_e32 v32, v0
	v_mov_b32_e32 v33, v0
	v_mov_b32_e32 v34, v0
	v_mov_b32_e32 v35, v0
	v_mov_b32_e32 v36, v0
	v_mov_b32_e32 v37, v0
	v_mov_b32_e32 v38, v0
	v_mov_b32_e32 v39, v0
	v_mov_b32_e32 v48, v0
	v_mov_b32_e32 v49, v0
	v_mov_b32_e32 v50, v0
	v_mov_b32_e32 v51, v0
	v_mov_b32_e32 v52, v0
	v_mov_b32_e32 v53, v0
	v_mov_b32_e32 v54, v0
	v_mov_b32_e32 v55, v0
	v_mov_b32_e32 v8, v0
	v_mov_b32_e32 v9, v0
	v_mov_b32_e32 v10, v0
	v_mov_b32_e32 v11, v0
	v_mov_b32_e32 v12, v0
	v_mov_b32_e32 v13, v0
	v_mov_b32_e32 v14, v0
	v_mov_b32_e32 v15, v0
	v_mov_b32_e32 v24, v0
	v_mov_b32_e32 v25, v0
	v_mov_b32_e32 v26, v0
	v_mov_b32_e32 v27, v0
	v_mov_b32_e32 v28, v0
	v_mov_b32_e32 v29, v0
	v_mov_b32_e32 v30, v0
	v_mov_b32_e32 v31, v0
	v_mov_b32_e32 v40, v0
	v_mov_b32_e32 v41, v0
	v_mov_b32_e32 v42, v0
	v_mov_b32_e32 v43, v0
	v_mov_b32_e32 v44, v0
	v_mov_b32_e32 v45, v0
	v_mov_b32_e32 v46, v0
	v_mov_b32_e32 v47, v0
	v_mov_b32_e32 v56, v0
	v_mov_b32_e32 v57, v0
	v_mov_b32_e32 v58, v0
	v_mov_b32_e32 v59, v0
	v_mov_b32_e32 v60, v0
	v_mov_b32_e32 v61, v0
	v_mov_b32_e32 v62, v0
	v_mov_b32_e32 v63, v0
	v_mov_b32_e32 v64, v0
	v_mov_b32_e32 v65, v0
	v_mov_b32_e32 v66, v0
	v_mov_b32_e32 v67, v0
	v_mov_b32_e32 v68, v0
	v_mov_b32_e32 v69, v0
	v_mov_b32_e32 v70, v0
	v_mov_b32_e32 v71, v0
	v_mov_b32_e32 v80, v0
	v_mov_b32_e32 v81, v0
	v_mov_b32_e32 v82, v0
	v_mov_b32_e32 v83, v0
	v_mov_b32_e32 v84, v0
	v_mov_b32_e32 v85, v0
	v_mov_b32_e32 v86, v0
	v_mov_b32_e32 v87, v0
	v_mov_b32_e32 v96, v0
	v_mov_b32_e32 v97, v0
	v_mov_b32_e32 v98, v0
	v_mov_b32_e32 v99, v0
	v_mov_b32_e32 v100, v0
	v_mov_b32_e32 v101, v0
	v_mov_b32_e32 v102, v0
	v_mov_b32_e32 v103, v0
	v_mov_b32_e32 v112, v0
	v_mov_b32_e32 v113, v0
	v_mov_b32_e32 v114, v0
	v_mov_b32_e32 v115, v0
	v_mov_b32_e32 v116, v0
	v_mov_b32_e32 v117, v0
	v_mov_b32_e32 v118, v0
	v_mov_b32_e32 v119, v0
	v_mov_b32_e32 v72, v0
	v_mov_b32_e32 v73, v0
	v_mov_b32_e32 v74, v0
	v_mov_b32_e32 v75, v0
	v_mov_b32_e32 v76, v0
	v_mov_b32_e32 v77, v0
	v_mov_b32_e32 v78, v0
	v_mov_b32_e32 v79, v0
	v_mov_b32_e32 v88, v0
	v_mov_b32_e32 v89, v0
	v_mov_b32_e32 v90, v0
	v_mov_b32_e32 v91, v0
	v_mov_b32_e32 v92, v0
	v_mov_b32_e32 v93, v0
	v_mov_b32_e32 v94, v0
	v_mov_b32_e32 v95, v0
	v_mov_b32_e32 v104, v0
	v_mov_b32_e32 v105, v0
	v_mov_b32_e32 v106, v0
	v_mov_b32_e32 v107, v0
	v_mov_b32_e32 v108, v0
	v_mov_b32_e32 v109, v0
	v_mov_b32_e32 v110, v0
	v_mov_b32_e32 v111, v0
	v_mov_b32_e32 v120, v0
	v_mov_b32_e32 v121, v0
	v_mov_b32_e32 v122, v0
	v_mov_b32_e32 v123, v0
	v_mov_b32_e32 v124, v0
	v_mov_b32_e32 v125, v0
	v_mov_b32_e32 v126, v0
	v_mov_b32_e32 v127, v0
	v_add_u32_e32 v148, 0x80, v128
	v_add_u32_e32 v149, 0x80, v130
	.p2align	6
	s_nop 0

.LBB0_987:
	s_ashr_i32 s19, s18, 31
	s_lshl_b64 s[6:7], s[18:19], 19
	s_add_u32 s20, s34, s6
	s_addc_u32 s21, s35, s7
	s_and_b64 s[6:7], s[4:5], exec
	s_cselect_b32 s19, s21, s29
	s_cselect_b32 s49, s20, s28
	s_ashr_i32 s17, s16, 31
	s_lshl_b64 s[6:7], s[16:17], 19
	s_add_u32 s22, s36, s6
	s_addc_u32 s23, s37, s7
	s_and_b64 s[6:7], s[4:5], exec
	s_cselect_b32 s17, s23, s27
	s_cselect_b32 s50, s22, s26
	s_add_u32 s51, s26, 0x100
	s_addc_u32 s52, s27, 0
	s_add_u32 s6, s28, 0x40080
	v_mov_b32_e32 v0, 0
	s_addc_u32 s7, s29, 0
	s_mov_b32 s53, -2
	v_mov_b32_e32 v1, v0
	v_mov_b32_e32 v2, v0
	v_mov_b32_e32 v3, v0
	v_mov_b32_e32 v4, v0
	v_mov_b32_e32 v5, v0
	v_mov_b32_e32 v6, v0
	v_mov_b32_e32 v7, v0
	v_mov_b32_e32 v16, v0
	v_mov_b32_e32 v17, v0
	v_mov_b32_e32 v18, v0
	v_mov_b32_e32 v19, v0
	v_mov_b32_e32 v20, v0
	v_mov_b32_e32 v21, v0
	v_mov_b32_e32 v22, v0
	v_mov_b32_e32 v23, v0
	v_mov_b32_e32 v32, v0
	v_mov_b32_e32 v33, v0
	v_mov_b32_e32 v34, v0
	v_mov_b32_e32 v35, v0
	v_mov_b32_e32 v36, v0
	v_mov_b32_e32 v37, v0
	v_mov_b32_e32 v38, v0
	v_mov_b32_e32 v39, v0
	v_mov_b32_e32 v48, v0
	v_mov_b32_e32 v49, v0
	v_mov_b32_e32 v50, v0
	v_mov_b32_e32 v51, v0
	v_mov_b32_e32 v52, v0
	v_mov_b32_e32 v53, v0
	v_mov_b32_e32 v54, v0
	v_mov_b32_e32 v55, v0
	v_mov_b32_e32 v8, v0
	v_mov_b32_e32 v9, v0
	v_mov_b32_e32 v10, v0
	v_mov_b32_e32 v11, v0
	v_mov_b32_e32 v12, v0
	v_mov_b32_e32 v13, v0
	v_mov_b32_e32 v14, v0
	v_mov_b32_e32 v15, v0
	v_mov_b32_e32 v24, v0
	v_mov_b32_e32 v25, v0
	v_mov_b32_e32 v26, v0
	v_mov_b32_e32 v27, v0
	v_mov_b32_e32 v28, v0
	v_mov_b32_e32 v29, v0
	v_mov_b32_e32 v30, v0
	v_mov_b32_e32 v31, v0
	v_mov_b32_e32 v40, v0
	v_mov_b32_e32 v41, v0
	v_mov_b32_e32 v42, v0
	v_mov_b32_e32 v43, v0
	v_mov_b32_e32 v44, v0
	v_mov_b32_e32 v45, v0
	v_mov_b32_e32 v46, v0
	v_mov_b32_e32 v47, v0
	v_mov_b32_e32 v56, v0
	v_mov_b32_e32 v57, v0
	v_mov_b32_e32 v58, v0
	v_mov_b32_e32 v59, v0
	v_mov_b32_e32 v60, v0
	v_mov_b32_e32 v61, v0
	v_mov_b32_e32 v62, v0
	v_mov_b32_e32 v63, v0
	v_mov_b32_e32 v64, v0
	v_mov_b32_e32 v65, v0
	v_mov_b32_e32 v66, v0
	v_mov_b32_e32 v67, v0
	v_mov_b32_e32 v68, v0
	v_mov_b32_e32 v69, v0
	v_mov_b32_e32 v70, v0
	v_mov_b32_e32 v71, v0
	v_mov_b32_e32 v80, v0
	v_mov_b32_e32 v81, v0
	v_mov_b32_e32 v82, v0
	v_mov_b32_e32 v83, v0
	v_mov_b32_e32 v84, v0
	v_mov_b32_e32 v85, v0
	v_mov_b32_e32 v86, v0
	v_mov_b32_e32 v87, v0
	v_mov_b32_e32 v96, v0
	v_mov_b32_e32 v97, v0
	v_mov_b32_e32 v98, v0
	v_mov_b32_e32 v99, v0
	v_mov_b32_e32 v100, v0
	v_mov_b32_e32 v101, v0
	v_mov_b32_e32 v102, v0
	v_mov_b32_e32 v103, v0
	v_mov_b32_e32 v112, v0
	v_mov_b32_e32 v113, v0
	v_mov_b32_e32 v114, v0
	v_mov_b32_e32 v115, v0
	v_mov_b32_e32 v116, v0
	v_mov_b32_e32 v117, v0
	v_mov_b32_e32 v118, v0
	v_mov_b32_e32 v119, v0
	v_mov_b32_e32 v72, v0
	v_mov_b32_e32 v73, v0
	v_mov_b32_e32 v74, v0
	v_mov_b32_e32 v75, v0
	v_mov_b32_e32 v76, v0
	v_mov_b32_e32 v77, v0
	v_mov_b32_e32 v78, v0
	v_mov_b32_e32 v79, v0
	v_mov_b32_e32 v88, v0
	v_mov_b32_e32 v89, v0
	v_mov_b32_e32 v90, v0
	v_mov_b32_e32 v91, v0
	v_mov_b32_e32 v92, v0
	v_mov_b32_e32 v93, v0
	v_mov_b32_e32 v94, v0
	v_mov_b32_e32 v95, v0
	v_mov_b32_e32 v104, v0
	v_mov_b32_e32 v105, v0
	v_mov_b32_e32 v106, v0
	v_mov_b32_e32 v107, v0
	v_mov_b32_e32 v108, v0
	v_mov_b32_e32 v109, v0
	v_mov_b32_e32 v110, v0
	v_mov_b32_e32 v111, v0
	v_mov_b32_e32 v120, v0
	v_mov_b32_e32 v121, v0
	v_mov_b32_e32 v122, v0
	v_mov_b32_e32 v123, v0
	v_mov_b32_e32 v124, v0
	v_mov_b32_e32 v125, v0
	v_mov_b32_e32 v126, v0
	v_mov_b32_e32 v127, v0
	v_add_u32_e32 v204, 0x80, v128
	v_add_u32_e32 v205, 0x80, v130
	v_add_u32_e32 v220, 0x80, v132
	v_add_u32_e32 v221, 0x80, v134
	.p2align	6
	s_nop 0

.LBB0_1192:
	s_ashr_i32 s17, s16, 31
	s_lshl_b64 s[18:19], s[16:17], 18
	s_add_u32 s18, s6, s18
	s_addc_u32 s19, s7, s19
	s_and_b64 s[20:21], s[4:5], exec
	s_cselect_b32 s17, s19, s27
	s_cselect_b32 s46, s18, s26
	s_ashr_i32 s15, s14, 31
	s_lshl_b64 s[20:21], s[14:15], 18
	s_add_u32 s20, s34, s20
	s_addc_u32 s21, s35, s21
	s_and_b64 s[28:29], s[4:5], exec
	s_cselect_b32 s15, s21, s25
	s_cselect_b32 s47, s20, s24
	s_add_u32 s48, s24, 0x100
	s_addc_u32 s49, s25, 0
	s_add_u32 s24, s26, 0x20080
	v_mov_b32_e32 v0, 0
	s_addc_u32 s25, s27, 0
	s_mov_b32 s50, -2
	v_mov_b32_e32 v1, v0
	v_mov_b32_e32 v2, v0
	v_mov_b32_e32 v3, v0
	v_mov_b32_e32 v4, v0
	v_mov_b32_e32 v5, v0
	v_mov_b32_e32 v6, v0
	v_mov_b32_e32 v7, v0
	v_mov_b32_e32 v16, v0
	v_mov_b32_e32 v17, v0
	v_mov_b32_e32 v18, v0
	v_mov_b32_e32 v19, v0
	v_mov_b32_e32 v20, v0
	v_mov_b32_e32 v21, v0
	v_mov_b32_e32 v22, v0
	v_mov_b32_e32 v23, v0
	v_mov_b32_e32 v32, v0
	v_mov_b32_e32 v33, v0
	v_mov_b32_e32 v34, v0
	v_mov_b32_e32 v35, v0
	v_mov_b32_e32 v36, v0
	v_mov_b32_e32 v37, v0
	v_mov_b32_e32 v38, v0
	v_mov_b32_e32 v39, v0
	v_mov_b32_e32 v48, v0
	v_mov_b32_e32 v49, v0
	v_mov_b32_e32 v50, v0
	v_mov_b32_e32 v51, v0
	v_mov_b32_e32 v52, v0
	v_mov_b32_e32 v53, v0
	v_mov_b32_e32 v54, v0
	v_mov_b32_e32 v55, v0
	v_mov_b32_e32 v8, v0
	v_mov_b32_e32 v9, v0
	v_mov_b32_e32 v10, v0
	v_mov_b32_e32 v11, v0
	v_mov_b32_e32 v12, v0
	v_mov_b32_e32 v13, v0
	v_mov_b32_e32 v14, v0
	v_mov_b32_e32 v15, v0
	v_mov_b32_e32 v24, v0
	v_mov_b32_e32 v25, v0
	v_mov_b32_e32 v26, v0
	v_mov_b32_e32 v27, v0
	v_mov_b32_e32 v28, v0
	v_mov_b32_e32 v29, v0
	v_mov_b32_e32 v30, v0
	v_mov_b32_e32 v31, v0
	v_mov_b32_e32 v40, v0
	v_mov_b32_e32 v41, v0
	v_mov_b32_e32 v42, v0
	v_mov_b32_e32 v43, v0
	v_mov_b32_e32 v44, v0
	v_mov_b32_e32 v45, v0
	v_mov_b32_e32 v46, v0
	v_mov_b32_e32 v47, v0
	v_mov_b32_e32 v56, v0
	v_mov_b32_e32 v57, v0
	v_mov_b32_e32 v58, v0
	v_mov_b32_e32 v59, v0
	v_mov_b32_e32 v60, v0
	v_mov_b32_e32 v61, v0
	v_mov_b32_e32 v62, v0
	v_mov_b32_e32 v63, v0
	v_mov_b32_e32 v64, v0
	v_mov_b32_e32 v65, v0
	v_mov_b32_e32 v66, v0
	v_mov_b32_e32 v67, v0
	v_mov_b32_e32 v68, v0
	v_mov_b32_e32 v69, v0
	v_mov_b32_e32 v70, v0
	v_mov_b32_e32 v71, v0
	v_mov_b32_e32 v80, v0
	v_mov_b32_e32 v81, v0
	v_mov_b32_e32 v82, v0
	v_mov_b32_e32 v83, v0
	v_mov_b32_e32 v84, v0
	v_mov_b32_e32 v85, v0
	v_mov_b32_e32 v86, v0
	v_mov_b32_e32 v87, v0
	v_mov_b32_e32 v96, v0
	v_mov_b32_e32 v97, v0
	v_mov_b32_e32 v98, v0
	v_mov_b32_e32 v99, v0
	v_mov_b32_e32 v100, v0
	v_mov_b32_e32 v101, v0
	v_mov_b32_e32 v102, v0
	v_mov_b32_e32 v103, v0
	v_mov_b32_e32 v112, v0
	v_mov_b32_e32 v113, v0
	v_mov_b32_e32 v114, v0
	v_mov_b32_e32 v115, v0
	v_mov_b32_e32 v116, v0
	v_mov_b32_e32 v117, v0
	v_mov_b32_e32 v118, v0
	v_mov_b32_e32 v119, v0
	v_mov_b32_e32 v72, v0
	v_mov_b32_e32 v73, v0
	v_mov_b32_e32 v74, v0
	v_mov_b32_e32 v75, v0
	v_mov_b32_e32 v76, v0
	v_mov_b32_e32 v77, v0
	v_mov_b32_e32 v78, v0
	v_mov_b32_e32 v79, v0
	v_mov_b32_e32 v88, v0
	v_mov_b32_e32 v89, v0
	v_mov_b32_e32 v90, v0
	v_mov_b32_e32 v91, v0
	v_mov_b32_e32 v92, v0
	v_mov_b32_e32 v93, v0
	v_mov_b32_e32 v94, v0
	v_mov_b32_e32 v95, v0
	v_mov_b32_e32 v104, v0
	v_mov_b32_e32 v105, v0
	v_mov_b32_e32 v106, v0
	v_mov_b32_e32 v107, v0
	v_mov_b32_e32 v108, v0
	v_mov_b32_e32 v109, v0
	v_mov_b32_e32 v110, v0
	v_mov_b32_e32 v111, v0
	v_mov_b32_e32 v120, v0
	v_mov_b32_e32 v121, v0
	v_mov_b32_e32 v122, v0
	v_mov_b32_e32 v123, v0
	v_mov_b32_e32 v124, v0
	v_mov_b32_e32 v125, v0
	v_mov_b32_e32 v126, v0
	v_mov_b32_e32 v127, v0
	v_add_u32_e32 v216, 0x80, v128
	v_add_u32_e32 v217, 0x80, v130
	v_add_u32_e32 v218, 0x80, v132
	v_add_u32_e32 v219, 0x80, v134
	.p2align	6
	s_nop 0

.LBB0_1364:
	s_ashr_i32 s19, s18, 31
	s_lshl_b64 s[20:21], s[18:19], 19
	s_add_u32 s20, s34, s20
	s_addc_u32 s21, s35, s21
	s_and_b64 s[22:23], s[4:5], exec
	s_cselect_b32 s19, s21, s27
	s_cselect_b32 s49, s20, s26
	s_ashr_i32 s17, s16, 31
	s_lshl_b64 s[22:23], s[16:17], 19
	s_add_u32 s22, s36, s22
	s_addc_u32 s23, s37, s23
	s_and_b64 s[28:29], s[4:5], exec
	s_cselect_b32 s17, s23, s25
	s_cselect_b32 s50, s22, s24
	s_add_u32 s51, s24, 0x100
	s_addc_u32 s52, s25, 0
	s_add_u32 s24, s26, 0x40080
	v_mov_b32_e32 v0, 0
	s_addc_u32 s25, s27, 0
	s_mov_b32 s53, -2
	v_mov_b32_e32 v1, v0
	v_mov_b32_e32 v2, v0
	v_mov_b32_e32 v3, v0
	v_mov_b32_e32 v4, v0
	v_mov_b32_e32 v5, v0
	v_mov_b32_e32 v6, v0
	v_mov_b32_e32 v7, v0
	v_mov_b32_e32 v16, v0
	v_mov_b32_e32 v17, v0
	v_mov_b32_e32 v18, v0
	v_mov_b32_e32 v19, v0
	v_mov_b32_e32 v20, v0
	v_mov_b32_e32 v21, v0
	v_mov_b32_e32 v22, v0
	v_mov_b32_e32 v23, v0
	v_mov_b32_e32 v32, v0
	v_mov_b32_e32 v33, v0
	v_mov_b32_e32 v34, v0
	v_mov_b32_e32 v35, v0
	v_mov_b32_e32 v36, v0
	v_mov_b32_e32 v37, v0
	v_mov_b32_e32 v38, v0
	v_mov_b32_e32 v39, v0
	v_mov_b32_e32 v48, v0
	v_mov_b32_e32 v49, v0
	v_mov_b32_e32 v50, v0
	v_mov_b32_e32 v51, v0
	v_mov_b32_e32 v52, v0
	v_mov_b32_e32 v53, v0
	v_mov_b32_e32 v54, v0
	v_mov_b32_e32 v55, v0
	v_mov_b32_e32 v8, v0
	v_mov_b32_e32 v9, v0
	v_mov_b32_e32 v10, v0
	v_mov_b32_e32 v11, v0
	v_mov_b32_e32 v12, v0
	v_mov_b32_e32 v13, v0
	v_mov_b32_e32 v14, v0
	v_mov_b32_e32 v15, v0
	v_mov_b32_e32 v24, v0
	v_mov_b32_e32 v25, v0
	v_mov_b32_e32 v26, v0
	v_mov_b32_e32 v27, v0
	v_mov_b32_e32 v28, v0
	v_mov_b32_e32 v29, v0
	v_mov_b32_e32 v30, v0
	v_mov_b32_e32 v31, v0
	v_mov_b32_e32 v40, v0
	v_mov_b32_e32 v41, v0
	v_mov_b32_e32 v42, v0
	v_mov_b32_e32 v43, v0
	v_mov_b32_e32 v44, v0
	v_mov_b32_e32 v45, v0
	v_mov_b32_e32 v46, v0
	v_mov_b32_e32 v47, v0
	v_mov_b32_e32 v56, v0
	v_mov_b32_e32 v57, v0
	v_mov_b32_e32 v58, v0
	v_mov_b32_e32 v59, v0
	v_mov_b32_e32 v60, v0
	v_mov_b32_e32 v61, v0
	v_mov_b32_e32 v62, v0
	v_mov_b32_e32 v63, v0
	v_mov_b32_e32 v64, v0
	v_mov_b32_e32 v65, v0
	v_mov_b32_e32 v66, v0
	v_mov_b32_e32 v67, v0
	v_mov_b32_e32 v68, v0
	v_mov_b32_e32 v69, v0
	v_mov_b32_e32 v70, v0
	v_mov_b32_e32 v71, v0
	v_mov_b32_e32 v80, v0
	v_mov_b32_e32 v81, v0
	v_mov_b32_e32 v82, v0
	v_mov_b32_e32 v83, v0
	v_mov_b32_e32 v84, v0
	v_mov_b32_e32 v85, v0
	v_mov_b32_e32 v86, v0
	v_mov_b32_e32 v87, v0
	v_mov_b32_e32 v96, v0
	v_mov_b32_e32 v97, v0
	v_mov_b32_e32 v98, v0
	v_mov_b32_e32 v99, v0
	v_mov_b32_e32 v100, v0
	v_mov_b32_e32 v101, v0
	v_mov_b32_e32 v102, v0
	v_mov_b32_e32 v103, v0
	v_mov_b32_e32 v112, v0
	v_mov_b32_e32 v113, v0
	v_mov_b32_e32 v114, v0
	v_mov_b32_e32 v115, v0
	v_mov_b32_e32 v116, v0
	v_mov_b32_e32 v117, v0
	v_mov_b32_e32 v118, v0
	v_mov_b32_e32 v119, v0
	v_mov_b32_e32 v72, v0
	v_mov_b32_e32 v73, v0
	v_mov_b32_e32 v74, v0
	v_mov_b32_e32 v75, v0
	v_mov_b32_e32 v76, v0
	v_mov_b32_e32 v77, v0
	v_mov_b32_e32 v78, v0
	v_mov_b32_e32 v79, v0
	v_mov_b32_e32 v88, v0
	v_mov_b32_e32 v89, v0
	v_mov_b32_e32 v90, v0
	v_mov_b32_e32 v91, v0
	v_mov_b32_e32 v92, v0
	v_mov_b32_e32 v93, v0
	v_mov_b32_e32 v94, v0
	v_mov_b32_e32 v95, v0
	v_mov_b32_e32 v104, v0
	v_mov_b32_e32 v105, v0
	v_mov_b32_e32 v106, v0
	v_mov_b32_e32 v107, v0
	v_mov_b32_e32 v108, v0
	v_mov_b32_e32 v109, v0
	v_mov_b32_e32 v110, v0
	v_mov_b32_e32 v111, v0
	v_mov_b32_e32 v120, v0
	v_mov_b32_e32 v121, v0
	v_mov_b32_e32 v122, v0
	v_mov_b32_e32 v123, v0
	v_mov_b32_e32 v124, v0
	v_mov_b32_e32 v125, v0
	v_mov_b32_e32 v126, v0
	v_mov_b32_e32 v127, v0
	v_add_u32_e32 v204, 0x80, v128
	v_add_u32_e32 v205, 0x80, v130
	v_add_u32_e32 v220, 0x80, v132
	v_add_u32_e32 v221, 0x80, v134
	.p2align	6
	s_nop 0

.LBB0_1560:
	s_ashr_i32 s29, s28, 31
	s_lshl_b64 s[30:31], s[28:29], 19
	s_add_u32 s30, s12, s30
	s_addc_u32 s31, s13, s31
	s_and_b64 s[34:35], s[6:7], exec
	s_cselect_b32 s3, s31, s39
	s_cselect_b32 s29, s30, s38
	s_ashr_i32 s27, s26, 31
	s_lshl_b64 s[34:35], s[26:27], 19
	s_add_u32 s34, s43, s34
	s_addc_u32 s35, s44, s35
	s_and_b64 s[40:41], s[6:7], exec
	s_cselect_b32 s27, s35, s37
	s_cselect_b32 s58, s34, s36
	s_add_u32 s59, s36, 0x100
	s_addc_u32 s60, s37, 0
	s_add_u32 s36, s38, 0x40080
	v_mov_b32_e32 v0, 0
	s_addc_u32 s37, s39, 0
	s_mov_b32 s61, -2
	v_mov_b32_e32 v1, v0
	v_mov_b32_e32 v2, v0
	v_mov_b32_e32 v3, v0
	v_mov_b32_e32 v4, v0
	v_mov_b32_e32 v5, v0
	v_mov_b32_e32 v6, v0
	v_mov_b32_e32 v7, v0
	v_mov_b32_e32 v16, v0
	v_mov_b32_e32 v17, v0
	v_mov_b32_e32 v18, v0
	v_mov_b32_e32 v19, v0
	v_mov_b32_e32 v20, v0
	v_mov_b32_e32 v21, v0
	v_mov_b32_e32 v22, v0
	v_mov_b32_e32 v23, v0
	v_mov_b32_e32 v32, v0
	v_mov_b32_e32 v33, v0
	v_mov_b32_e32 v34, v0
	v_mov_b32_e32 v35, v0
	v_mov_b32_e32 v36, v0
	v_mov_b32_e32 v37, v0
	v_mov_b32_e32 v38, v0
	v_mov_b32_e32 v39, v0
	v_mov_b32_e32 v48, v0
	v_mov_b32_e32 v49, v0
	v_mov_b32_e32 v50, v0
	v_mov_b32_e32 v51, v0
	v_mov_b32_e32 v52, v0
	v_mov_b32_e32 v53, v0
	v_mov_b32_e32 v54, v0
	v_mov_b32_e32 v55, v0
	v_mov_b32_e32 v8, v0
	v_mov_b32_e32 v9, v0
	v_mov_b32_e32 v10, v0
	v_mov_b32_e32 v11, v0
	v_mov_b32_e32 v12, v0
	v_mov_b32_e32 v13, v0
	v_mov_b32_e32 v14, v0
	v_mov_b32_e32 v15, v0
	v_mov_b32_e32 v24, v0
	v_mov_b32_e32 v25, v0
	v_mov_b32_e32 v26, v0
	v_mov_b32_e32 v27, v0
	v_mov_b32_e32 v28, v0
	v_mov_b32_e32 v29, v0
	v_mov_b32_e32 v30, v0
	v_mov_b32_e32 v31, v0
	v_mov_b32_e32 v40, v0
	v_mov_b32_e32 v41, v0
	v_mov_b32_e32 v42, v0
	v_mov_b32_e32 v43, v0
	v_mov_b32_e32 v44, v0
	v_mov_b32_e32 v45, v0
	v_mov_b32_e32 v46, v0
	v_mov_b32_e32 v47, v0
	v_mov_b32_e32 v56, v0
	v_mov_b32_e32 v57, v0
	v_mov_b32_e32 v58, v0
	v_mov_b32_e32 v59, v0
	v_mov_b32_e32 v60, v0
	v_mov_b32_e32 v61, v0
	v_mov_b32_e32 v62, v0
	v_mov_b32_e32 v63, v0
	v_mov_b32_e32 v64, v0
	v_mov_b32_e32 v65, v0
	v_mov_b32_e32 v66, v0
	v_mov_b32_e32 v67, v0
	v_mov_b32_e32 v68, v0
	v_mov_b32_e32 v69, v0
	v_mov_b32_e32 v70, v0
	v_mov_b32_e32 v71, v0
	v_mov_b32_e32 v80, v0
	v_mov_b32_e32 v81, v0
	v_mov_b32_e32 v82, v0
	v_mov_b32_e32 v83, v0
	v_mov_b32_e32 v84, v0
	v_mov_b32_e32 v85, v0
	v_mov_b32_e32 v86, v0
	v_mov_b32_e32 v87, v0
	v_mov_b32_e32 v96, v0
	v_mov_b32_e32 v97, v0
	v_mov_b32_e32 v98, v0
	v_mov_b32_e32 v99, v0
	v_mov_b32_e32 v100, v0
	v_mov_b32_e32 v101, v0
	v_mov_b32_e32 v102, v0
	v_mov_b32_e32 v103, v0
	v_mov_b32_e32 v112, v0
	v_mov_b32_e32 v113, v0
	v_mov_b32_e32 v114, v0
	v_mov_b32_e32 v115, v0
	v_mov_b32_e32 v116, v0
	v_mov_b32_e32 v117, v0
	v_mov_b32_e32 v118, v0
	v_mov_b32_e32 v119, v0
	v_mov_b32_e32 v72, v0
	v_mov_b32_e32 v73, v0
	v_mov_b32_e32 v74, v0
	v_mov_b32_e32 v75, v0
	v_mov_b32_e32 v76, v0
	v_mov_b32_e32 v77, v0
	v_mov_b32_e32 v78, v0
	v_mov_b32_e32 v79, v0
	v_mov_b32_e32 v88, v0
	v_mov_b32_e32 v89, v0
	v_mov_b32_e32 v90, v0
	v_mov_b32_e32 v91, v0
	v_mov_b32_e32 v92, v0
	v_mov_b32_e32 v93, v0
	v_mov_b32_e32 v94, v0
	v_mov_b32_e32 v95, v0
	v_mov_b32_e32 v104, v0
	v_mov_b32_e32 v105, v0
	v_mov_b32_e32 v106, v0
	v_mov_b32_e32 v107, v0
	v_mov_b32_e32 v108, v0
	v_mov_b32_e32 v109, v0
	v_mov_b32_e32 v110, v0
	v_mov_b32_e32 v111, v0
	v_mov_b32_e32 v120, v0
	v_mov_b32_e32 v121, v0
	v_mov_b32_e32 v122, v0
	v_mov_b32_e32 v123, v0
	v_mov_b32_e32 v124, v0
	v_mov_b32_e32 v125, v0
	v_mov_b32_e32 v126, v0
	v_mov_b32_e32 v127, v0
	v_add_u32_e32 v204, 0x80, v128
	v_add_u32_e32 v205, 0x80, v130
	.p2align	6
	s_nop 0

.LBB0_1645:
	s_ashr_i32 s19, s18, 31
	s_lshl_b64 s[20:21], s[18:19], 19
	s_add_u32 s20, s8, s20
	s_addc_u32 s21, s9, s21
	s_and_b64 s[22:23], s[4:5], exec
	s_cselect_b32 s19, s21, s27
	s_cselect_b32 s50, s20, s26
	s_ashr_i32 s17, s16, 31
	s_lshl_b64 s[22:23], s[16:17], 19
	s_add_u32 s22, s31, s22
	s_addc_u32 s23, s34, s23
	s_and_b64 s[28:29], s[4:5], exec
	s_cselect_b32 s17, s23, s25
	s_cselect_b32 s51, s22, s24
	s_add_u32 s52, s24, 0x100
	s_addc_u32 s53, s25, 0
	s_add_u32 s24, s26, 0x40080
	v_mov_b32_e32 v0, 0
	s_addc_u32 s25, s27, 0
	s_mov_b32 s54, -2
	v_mov_b32_e32 v1, v0
	v_mov_b32_e32 v2, v0
	v_mov_b32_e32 v3, v0
	v_mov_b32_e32 v4, v0
	v_mov_b32_e32 v5, v0
	v_mov_b32_e32 v6, v0
	v_mov_b32_e32 v7, v0
	v_mov_b32_e32 v16, v0
	v_mov_b32_e32 v17, v0
	v_mov_b32_e32 v18, v0
	v_mov_b32_e32 v19, v0
	v_mov_b32_e32 v20, v0
	v_mov_b32_e32 v21, v0
	v_mov_b32_e32 v22, v0
	v_mov_b32_e32 v23, v0
	v_mov_b32_e32 v32, v0
	v_mov_b32_e32 v33, v0
	v_mov_b32_e32 v34, v0
	v_mov_b32_e32 v35, v0
	v_mov_b32_e32 v36, v0
	v_mov_b32_e32 v37, v0
	v_mov_b32_e32 v38, v0
	v_mov_b32_e32 v39, v0
	v_mov_b32_e32 v48, v0
	v_mov_b32_e32 v49, v0
	v_mov_b32_e32 v50, v0
	v_mov_b32_e32 v51, v0
	v_mov_b32_e32 v52, v0
	v_mov_b32_e32 v53, v0
	v_mov_b32_e32 v54, v0
	v_mov_b32_e32 v55, v0
	v_mov_b32_e32 v8, v0
	v_mov_b32_e32 v9, v0
	v_mov_b32_e32 v10, v0
	v_mov_b32_e32 v11, v0
	v_mov_b32_e32 v12, v0
	v_mov_b32_e32 v13, v0
	v_mov_b32_e32 v14, v0
	v_mov_b32_e32 v15, v0
	v_mov_b32_e32 v24, v0
	v_mov_b32_e32 v25, v0
	v_mov_b32_e32 v26, v0
	v_mov_b32_e32 v27, v0
	v_mov_b32_e32 v28, v0
	v_mov_b32_e32 v29, v0
	v_mov_b32_e32 v30, v0
	v_mov_b32_e32 v31, v0
	v_mov_b32_e32 v40, v0
	v_mov_b32_e32 v41, v0
	v_mov_b32_e32 v42, v0
	v_mov_b32_e32 v43, v0
	v_mov_b32_e32 v44, v0
	v_mov_b32_e32 v45, v0
	v_mov_b32_e32 v46, v0
	v_mov_b32_e32 v47, v0
	v_mov_b32_e32 v56, v0
	v_mov_b32_e32 v57, v0
	v_mov_b32_e32 v58, v0
	v_mov_b32_e32 v59, v0
	v_mov_b32_e32 v60, v0
	v_mov_b32_e32 v61, v0
	v_mov_b32_e32 v62, v0
	v_mov_b32_e32 v63, v0
	v_mov_b32_e32 v64, v0
	v_mov_b32_e32 v65, v0
	v_mov_b32_e32 v66, v0
	v_mov_b32_e32 v67, v0
	v_mov_b32_e32 v68, v0
	v_mov_b32_e32 v69, v0
	v_mov_b32_e32 v70, v0
	v_mov_b32_e32 v71, v0
	v_mov_b32_e32 v80, v0
	v_mov_b32_e32 v81, v0
	v_mov_b32_e32 v82, v0
	v_mov_b32_e32 v83, v0
	v_mov_b32_e32 v84, v0
	v_mov_b32_e32 v85, v0
	v_mov_b32_e32 v86, v0
	v_mov_b32_e32 v87, v0
	v_mov_b32_e32 v96, v0
	v_mov_b32_e32 v97, v0
	v_mov_b32_e32 v98, v0
	v_mov_b32_e32 v99, v0
	v_mov_b32_e32 v100, v0
	v_mov_b32_e32 v101, v0
	v_mov_b32_e32 v102, v0
	v_mov_b32_e32 v103, v0
	v_mov_b32_e32 v112, v0
	v_mov_b32_e32 v113, v0
	v_mov_b32_e32 v114, v0
	v_mov_b32_e32 v115, v0
	v_mov_b32_e32 v116, v0
	v_mov_b32_e32 v117, v0
	v_mov_b32_e32 v118, v0
	v_mov_b32_e32 v119, v0
	v_mov_b32_e32 v72, v0
	v_mov_b32_e32 v73, v0
	v_mov_b32_e32 v74, v0
	v_mov_b32_e32 v75, v0
	v_mov_b32_e32 v76, v0
	v_mov_b32_e32 v77, v0
	v_mov_b32_e32 v78, v0
	v_mov_b32_e32 v79, v0
	v_mov_b32_e32 v88, v0
	v_mov_b32_e32 v89, v0
	v_mov_b32_e32 v90, v0
	v_mov_b32_e32 v91, v0
	v_mov_b32_e32 v92, v0
	v_mov_b32_e32 v93, v0
	v_mov_b32_e32 v94, v0
	v_mov_b32_e32 v95, v0
	v_mov_b32_e32 v104, v0
	v_mov_b32_e32 v105, v0
	v_mov_b32_e32 v106, v0
	v_mov_b32_e32 v107, v0
	v_mov_b32_e32 v108, v0
	v_mov_b32_e32 v109, v0
	v_mov_b32_e32 v110, v0
	v_mov_b32_e32 v111, v0
	v_mov_b32_e32 v120, v0
	v_mov_b32_e32 v121, v0
	v_mov_b32_e32 v122, v0
	v_mov_b32_e32 v123, v0
	v_mov_b32_e32 v124, v0
	v_mov_b32_e32 v125, v0
	v_mov_b32_e32 v126, v0
	v_mov_b32_e32 v127, v0
	v_add_u32_e32 v204, 0x80, v128
	v_add_u32_e32 v205, 0x80, v130
	v_add_u32_e32 v220, 0x80, v132
	v_add_u32_e32 v221, 0x80, v134
	.p2align	6
	s_nop 0

.LBB0_3040:
	s_ashr_i32 s29, s28, 31
	s_lshl_b64 s[30:31], s[28:29], 19
	s_add_u32 s30, s8, s30
	s_addc_u32 s31, s9, s31
	s_and_b64 s[34:35], s[6:7], exec
	s_cselect_b32 s3, s31, s39
	s_cselect_b32 s29, s30, s38
	s_ashr_i32 s27, s26, 31
	s_lshl_b64 s[34:35], s[26:27], 19
	s_add_u32 s34, s43, s34
	s_addc_u32 s35, s44, s35
	s_and_b64 s[40:41], s[6:7], exec
	s_cselect_b32 s27, s35, s37
	s_cselect_b32 s58, s34, s36
	s_add_u32 s59, s36, 0x100
	s_addc_u32 s60, s37, 0
	s_add_u32 s36, s38, 0x40080
	v_mov_b32_e32 v0, 0
	s_addc_u32 s37, s39, 0
	s_mov_b32 s61, -2
	v_mov_b32_e32 v1, v0
	v_mov_b32_e32 v2, v0
	v_mov_b32_e32 v3, v0
	v_mov_b32_e32 v4, v0
	v_mov_b32_e32 v5, v0
	v_mov_b32_e32 v6, v0
	v_mov_b32_e32 v7, v0
	v_mov_b32_e32 v16, v0
	v_mov_b32_e32 v17, v0
	v_mov_b32_e32 v18, v0
	v_mov_b32_e32 v19, v0
	v_mov_b32_e32 v20, v0
	v_mov_b32_e32 v21, v0
	v_mov_b32_e32 v22, v0
	v_mov_b32_e32 v23, v0
	v_mov_b32_e32 v32, v0
	v_mov_b32_e32 v33, v0
	v_mov_b32_e32 v34, v0
	v_mov_b32_e32 v35, v0
	v_mov_b32_e32 v36, v0
	v_mov_b32_e32 v37, v0
	v_mov_b32_e32 v38, v0
	v_mov_b32_e32 v39, v0
	v_mov_b32_e32 v48, v0
	v_mov_b32_e32 v49, v0
	v_mov_b32_e32 v50, v0
	v_mov_b32_e32 v51, v0
	v_mov_b32_e32 v52, v0
	v_mov_b32_e32 v53, v0
	v_mov_b32_e32 v54, v0
	v_mov_b32_e32 v55, v0
	v_mov_b32_e32 v8, v0
	v_mov_b32_e32 v9, v0
	v_mov_b32_e32 v10, v0
	v_mov_b32_e32 v11, v0
	v_mov_b32_e32 v12, v0
	v_mov_b32_e32 v13, v0
	v_mov_b32_e32 v14, v0
	v_mov_b32_e32 v15, v0
	v_mov_b32_e32 v24, v0
	v_mov_b32_e32 v25, v0
	v_mov_b32_e32 v26, v0
	v_mov_b32_e32 v27, v0
	v_mov_b32_e32 v28, v0
	v_mov_b32_e32 v29, v0
	v_mov_b32_e32 v30, v0
	v_mov_b32_e32 v31, v0
	v_mov_b32_e32 v40, v0
	v_mov_b32_e32 v41, v0
	v_mov_b32_e32 v42, v0
	v_mov_b32_e32 v43, v0
	v_mov_b32_e32 v44, v0
	v_mov_b32_e32 v45, v0
	v_mov_b32_e32 v46, v0
	v_mov_b32_e32 v47, v0
	v_mov_b32_e32 v56, v0
	v_mov_b32_e32 v57, v0
	v_mov_b32_e32 v58, v0
	v_mov_b32_e32 v59, v0
	v_mov_b32_e32 v60, v0
	v_mov_b32_e32 v61, v0
	v_mov_b32_e32 v62, v0
	v_mov_b32_e32 v63, v0
	v_mov_b32_e32 v64, v0
	v_mov_b32_e32 v65, v0
	v_mov_b32_e32 v66, v0
	v_mov_b32_e32 v67, v0
	v_mov_b32_e32 v68, v0
	v_mov_b32_e32 v69, v0
	v_mov_b32_e32 v70, v0
	v_mov_b32_e32 v71, v0
	v_mov_b32_e32 v80, v0
	v_mov_b32_e32 v81, v0
	v_mov_b32_e32 v82, v0
	v_mov_b32_e32 v83, v0
	v_mov_b32_e32 v84, v0
	v_mov_b32_e32 v85, v0
	v_mov_b32_e32 v86, v0
	v_mov_b32_e32 v87, v0
	v_mov_b32_e32 v96, v0
	v_mov_b32_e32 v97, v0
	v_mov_b32_e32 v98, v0
	v_mov_b32_e32 v99, v0
	v_mov_b32_e32 v100, v0
	v_mov_b32_e32 v101, v0
	v_mov_b32_e32 v102, v0
	v_mov_b32_e32 v103, v0
	v_mov_b32_e32 v112, v0
	v_mov_b32_e32 v113, v0
	v_mov_b32_e32 v114, v0
	v_mov_b32_e32 v115, v0
	v_mov_b32_e32 v116, v0
	v_mov_b32_e32 v117, v0
	v_mov_b32_e32 v118, v0
	v_mov_b32_e32 v119, v0
	v_mov_b32_e32 v72, v0
	v_mov_b32_e32 v73, v0
	v_mov_b32_e32 v74, v0
	v_mov_b32_e32 v75, v0
	v_mov_b32_e32 v76, v0
	v_mov_b32_e32 v77, v0
	v_mov_b32_e32 v78, v0
	v_mov_b32_e32 v79, v0
	v_mov_b32_e32 v88, v0
	v_mov_b32_e32 v89, v0
	v_mov_b32_e32 v90, v0
	v_mov_b32_e32 v91, v0
	v_mov_b32_e32 v92, v0
	v_mov_b32_e32 v93, v0
	v_mov_b32_e32 v94, v0
	v_mov_b32_e32 v95, v0
	v_mov_b32_e32 v104, v0
	v_mov_b32_e32 v105, v0
	v_mov_b32_e32 v106, v0
	v_mov_b32_e32 v107, v0
	v_mov_b32_e32 v108, v0
	v_mov_b32_e32 v109, v0
	v_mov_b32_e32 v110, v0
	v_mov_b32_e32 v111, v0
	v_mov_b32_e32 v120, v0
	v_mov_b32_e32 v121, v0
	v_mov_b32_e32 v122, v0
	v_mov_b32_e32 v123, v0
	v_mov_b32_e32 v124, v0
	v_mov_b32_e32 v125, v0
	v_mov_b32_e32 v126, v0
	v_mov_b32_e32 v127, v0
	v_add_u32_e32 v204, 0x80, v128
	v_add_u32_e32 v205, 0x80, v130
	.p2align	6
	s_nop 0
